# FFN-up GEMM: LDS half-tile layout with whole-cache-line DMA pieces (8 rows x 128 B) + XOR chunk swizzle
# speedup vs baseline: 1.0047x; 1.0047x over previous
.LBB0_1121:
	s_cmp_lt_i32 s44, 7
	s_cselect_b64 s[0:1], -1, 0
	s_cmp_gt_i32 s45, 6
	s_cselect_b64 s[2:3], -1, 0
	s_and_b64 s[0:1], s[0:1], s[2:3]
	s_andn2_b64 vcc, exec, s[0:1]
	s_cbranch_vccnz .LBB0_1204
	v_lshlrev_b32_e32 v1, 2, v0
	s_cmpk_gt_i32 s43, 0x5ab
	v_readfirstlane_b32 s1, v0
	s_cbranch_scc1 .LBB0_1142
	v_lshrrev_b32_e32 v4, 1, v0
	v_and_b32_e32 v13, 24, v4
	v_lshrrev_b32_e32 v4, 5, v0
	s_add_u32 s26, s68, 0x2a000000
	v_lshlrev_b32_e32 v2, 4, v0
	v_and_b32_e32 v3, 32, v0
	v_and_b32_e32 v4, 4, v4
	v_bfe_u32 v5, v0, 2, 2
	s_addc_u32 s27, s69, 0
	v_bfe_u32 v12, v0, 2, 4
	v_bitop3_b32 v10, v2, v3, 48 bitop3:0x6c
	v_and_b32_e32 v11, 64, v0
	v_or3_b32 v4, v4, v5, v13
	v_lshrrev_b32_e32 v5, 3, v0
	v_or_b32_e32 v14, 0x2000, v2
	s_add_u32 s28, s68, 0x4600000
	v_or_b32_e32 v3, v10, v11
	v_and_or_b32 v6, v5, 48, v12
	v_and_or_b32 v5, v5, 32, v4
	v_lshrrev_b32_e32 v2, 7, v14
	s_movk_i32 s0, 0x70
	s_addc_u32 s29, s69, 0
	v_lshl_or_b32 v132, v5, 12, v3
	v_and_or_b32 v5, v2, s0, v12
	s_movk_i32 s0, 0x60
	s_ashr_i32 s31, s43, 31
	v_and_or_b32 v2, v2, s0, v4
	s_lshr_b32 s0, s31, 29
	s_add_i32 s0, s43, s0
	s_and_b32 s2, s0, -8
	s_sub_i32 s2, s43, s2
	s_lshr_b32 s6, s1, 6
	s_mul_i32 s4, s2, 0xb5
	s_lshr_b32 s8, s1, 8
	s_lshl_b32 s30, s6, 10
	s_add_i32 s4, s4, 4
	s_ashr_i32 s0, s0, 3
	s_mul_i32 s3, s2, 0xb6
	s_cmp_lt_i32 s2, 4
	s_cselect_b32 s2, s3, s4
	s_add_i32 s2, s2, s0
	s_mul_hi_i32 s0, s2, 0x2e8ba2e9
	s_lshr_b32 s3, s0, 31
	s_ashr_i32 s0, s0, 6
	s_add_i32 s0, s0, s3
	s_lshl_b32 s4, s0, 3
	s_sub_i32 s3, 33, s4
	s_mulk_i32 s0, 0x160
	s_min_u32 s5, s3, 8
	s_sub_i32 s7, s2, s0
	v_lshl_or_b32 v134, v5, 12, v3
	s_sext_i32_i16 s0, s7
	v_cvt_f32_ubyte0_e32 v5, s5
	v_lshl_or_b32 v130, v6, 12, v3
	v_cvt_f32_i32_e32 v4, s0
	v_rcp_iflag_f32_e32 v6, v5
	v_lshl_or_b32 v136, v2, 12, v3
	s_ashr_i32 s0, s0, 30
	s_or_b32 s0, s0, 1
	v_mul_f32_e32 v2, v4, v6
	v_trunc_f32_e32 v2, v2
	v_fma_f32 v3, -v2, v5, v4
	v_cvt_i32_f32_e32 v2, v2
	v_cmp_ge_f32_e64 s[2:3], |v3|, v5
	s_and_b64 s[2:3], s[2:3], exec
	s_cselect_b32 s0, s0, 0
	v_readfirstlane_b32 s2, v2
	s_add_i32 s0, s2, s0
	s_mul_i32 s2, s0, s5
	s_sub_i32 s2, s7, s2
	s_sext_i32_i16 s2, s2
	s_add_i32 s18, s4, s2
	s_ashr_i32 s19, s18, 31
	s_bfe_i64 s[4:5], s[0:1], 0x100000
	s_lshl_b64 s[2:3], s[18:19], 20
	s_lshl_b64 s[4:5], s[4:5], 20
	s_add_u32 s22, s28, s4
	s_addc_u32 s23, s29, s5
	s_add_i32 s19, s30, 0
	s_add_i32 m0, s19, 0x10000
	v_mov_b32_e32 v133, 0
	v_lshrrev_b32_e32 v240, 6, v0
	v_bfe_u32 v241, v0, 3, 3
	v_and_b32_e32 v242, 7, v0
	v_lshrrev_b32_e32 v243, 1, v241
	v_and_b32_e32 v244, 1, v240
	v_lshl_or_b32 v243, v244, 2, v243
	v_xor_b32_e32 v242, v242, v243
	v_lshlrev_b32_e32 v242, 4, v242
	v_lshl_add_u32 v245, v240, 3, v241
	v_lshrrev_b32_e32 v246, 2, v240
	v_lshlrev_b32_e32 v246, 5, v246
	v_lshl_add_u32 v246, v244, 4, v246
	v_lshrrev_b32_e32 v247, 2, v241
	v_lshl_add_u32 v246, v247, 3, v246
	v_bfe_u32 v247, v240, 1, 1
	v_lshl_add_u32 v246, v247, 2, v246
	v_and_b32_e32 v247, 3, v241
	v_add_u32_e32 v246, v246, v247
	v_lshl_add_u32 v130, v245, 12, v242
	v_lshl_add_u32 v132, v246, 12, v242
	v_add_u32_e32 v134, 0x40000, v130
	v_add_u32_e32 v136, 0x40000, v132
	global_load_lds_dwordx4 v132, s[22:23]
	s_add_i32 m0, s19, 0x12000
	s_add_u32 s4, s22, 0x80000
	global_load_lds_dwordx4 v136, s[22:23]
	s_addc_u32 s5, s23, 0
	s_add_i32 m0, s19, 0x14000
	v_mov_b32_e32 v137, v133
	global_load_lds_dwordx4 v132, s[4:5]
	s_add_i32 m0, s19, 0x16000
	s_add_u32 s20, s26, s2
	s_addc_u32 s21, s27, s3
	s_add_i32 s33, s19, 0x2000
	global_load_lds_dwordx4 v136, s[4:5]
	s_mov_b32 m0, s19
	s_add_u32 s2, s20, 0x80000
	global_load_lds_dwordx4 v130, s[20:21]
	s_mov_b32 m0, s33
	s_addc_u32 s3, s21, 0
	s_add_i32 s34, s19, 0x4000
	global_load_lds_dwordx4 v134, s[20:21]
	s_mov_b32 m0, s34
	s_add_i32 s35, s19, 0x6000
	global_load_lds_dwordx4 v130, s[2:3]
	s_mov_b32 m0, s35
	v_mov_b32_e32 v131, v133
	global_load_lds_dwordx4 v134, s[2:3]
	v_mov_b32_e32 v135, v133
	s_cmp_eq_u32 s8, 1
	s_mov_b32 s36, 0
	v_lshl_add_u64 v[8:9], s[22:23], 0, v[132:133]
	v_lshl_add_u64 v[6:7], s[22:23], 0, v[136:137]
	v_lshl_add_u64 v[2:3], s[20:21], 0, v[130:131]
	s_cselect_b64 s[2:3], -1, 0
	s_cmp_lg_u32 s8, 1
	v_lshl_add_u64 v[4:5], s[20:21], 0, v[134:135]
	s_cbranch_scc1 .LBB0_1125
	s_barrier
.LBB0_1125:
	s_add_u32 s4, s68, 0x2c400000
	s_addc_u32 s5, s69, 0
	v_readlane_b32 s7, v254, 2
	s_lshl_b32 s6, s6, 5
	s_ashr_i32 s37, s7, 31
	s_and_b32 s12, s6, 0x60
	s_mov_b64 s[6:7], 0x80
	s_add_i32 m0, s19, 0x18000
	v_lshl_add_u64 v[8:9], v[8:9], 0, s[6:7]
	s_lshl_b32 s9, s8, 13
	s_lshl_b32 s13, s12, 7
	s_waitcnt vmcnt(2)
	s_barrier
	global_load_lds_dwordx4 v[8:9], off
	v_lshl_add_u64 v[6:7], v[6:7], 0, s[6:7]
	s_add_i32 m0, s19, 0x1a000
	s_add_i32 s38, s19, 0x8000
	s_add_i32 s39, s19, 0xa000
	global_load_lds_dwordx4 v[6:7], off
	v_lshl_add_u64 v[2:3], v[2:3], 0, s[6:7]
	s_mov_b32 m0, s38
	s_add_u32 s10, s22, 0x80080
	global_load_lds_dwordx4 v[2:3], off
	v_lshl_add_u64 v[2:3], v[4:5], 0, s[6:7]
	s_mov_b32 m0, s39
	s_addc_u32 s11, s23, 0
	global_load_lds_dwordx4 v[2:3], off
	s_add_i32 m0, s19, 0x1c000
	v_lshl_add_u64 v[2:3], s[10:11], 0, v[132:133]
	global_load_lds_dwordx4 v[2:3], off
	v_lshl_add_u64 v[2:3], s[10:11], 0, v[136:137]
	s_add_i32 m0, s19, 0x1e000
	s_sext_i32_i16 s43, s0
	global_load_lds_dwordx4 v[2:3], off
	v_and_b32_e32 v2, 15, v0
	v_lshlrev_b32_e32 v3, 1, v13
	v_lshlrev_b32_e32 v4, 6, v0
	s_movk_i32 s0, 0x3c0
	v_and_or_b32 v4, v4, s0, v3
	v_and_b32_e32 v5, 32, v1
	v_lshl_or_b32 v146, s8, 6, v2
	v_lshl_or_b32 v2, v2, 6, v3
	v_lshlrev_b32_e32 v3, 9, v0
	v_bitop3_b32 v147, s13, v4, v5 bitop3:0xf6
	v_and_b32_e32 v3, 0x30000, v3
	v_lshlrev_b32_e32 v4, 12, v12
	v_or3_b32 v3, v10, v3, v4
	v_add_u32_e32 v138, v3, v11
	v_lshlrev_b32_e32 v3, 5, v14
	s_waitcnt vmcnt(6)
	s_cmpk_lt_u32 s1, 0x100
	v_and_b32_e32 v3, 0x70000, v3
	v_bitop3_b32 v2, v2, s9, v5 bitop3:0xde
	s_cselect_b64 s[8:9], -1, 0
	v_or3_b32 v3, v10, v3, v4
	s_add_i32 s40, 0, 0x10000
	s_add_i32 s41, 0, 0x14000
	v_or_b32_e32 v148, s12, v13
	v_mov_b32_e32 v139, v133
	v_add_u32_e32 v140, v3, v11
	v_mov_b32_e32 v141, v133
	v_mov_b64_e32 v[142:143], 0x5ac
	v_mov_b64_e32 v[144:145], 0x5ab
	v_add_u32_e32 v149, s40, v147
	v_add_u32_e32 v150, s41, v147
	v_add_u32_e32 v151, 0, v2
	s_movk_i32 s42, 0x2c00
	s_barrier
	v_mov_b32_e32 v138, v130
	v_mov_b32_e32 v140, v134
	v_and_b32_e32 v240, 63, v0
	v_and_b32_e32 v241, 15, v240
	v_lshrrev_b32_e32 v242, 4, v240
	v_lshrrev_b32_e32 v243, 3, v241
	v_lshlrev_b32_e32 v243, 10, v243
	v_and_b32_e32 v244, 7, v241
	v_lshl_add_u32 v243, v244, 7, v243
	v_lshrrev_b32_e32 v244, 1, v241
	v_xor_b32_e32 v245, v242, v244
	v_lshl_add_u32 v245, v245, 4, v243
	v_xor_b32_e32 v246, 64, v245
	v_lshrrev_b32_e32 v247, 6, v0
	v_lshrrev_b32_e32 v244, 2, v247
	v_lshl_add_u32 v151, v244, 13, v245
	v_lshl_add_u32 v228, v244, 13, v246
	v_and_b32_e32 v244, 3, v247
	v_lshl_add_u32 v147, v244, 12, v245
	v_lshl_add_u32 v229, v244, 12, v246
	v_add_u32_e32 v149, s40, v147
	v_add_u32_e32 v230, s40, v229
	v_add_u32_e32 v150, s41, v147
	v_add_u32_e32 v231, s41, v229
	s_branch .LBB0_1128

.LBB0_1135:
	ds_read_b128 v[152:155], v149
	ds_read_b128 v[156:159], v230
	ds_read_b128 v[160:163], v149 offset:2048
	ds_read_b128 v[164:167], v230 offset:2048
	ds_read_b128 v[168:171], v150
	ds_read_b128 v[172:175], v231
	ds_read_b128 v[176:179], v150 offset:2048
	ds_read_b128 v[180:183], v231 offset:2048
	s_add_u32 s22, s20, 0xfff80080
	s_addc_u32 s23, s21, -1
	s_cmp_eq_u32 s48, 28
	s_cselect_b32 s25, s13, s23
	s_cselect_b32 s24, s44, s22
	s_cselect_b32 s23, s11, s47
	s_cselect_b32 s22, s45, s46
	s_add_i32 m0, s19, 0xc000
	ds_read_b128 v[184:187], v151
	ds_read_b128 v[188:191], v228
	ds_read_b128 v[192:195], v151 offset:2048
	ds_read_b128 v[196:199], v228 offset:2048
	ds_read_b128 v[200:203], v151 offset:4096
	ds_read_b128 v[204:207], v228 offset:4096
	ds_read_b128 v[208:211], v151 offset:6144
	ds_read_b128 v[212:215], v228 offset:6144
	global_load_lds_dwordx4 v138, s[20:21]
	s_add_i32 m0, s19, 0xe000
	s_nop 0
	global_load_lds_dwordx4 v140, s[20:21]
	s_waitcnt vmcnt(8)
	s_waitcnt lgkmcnt(0)
	s_barrier
	s_setprio 1
	s_waitcnt lgkmcnt(0)
	v_mfma_f32_16x16x32_bf16 v[126:129], v[152:155], v[184:187], v[126:129]
	v_mfma_f32_16x16x32_bf16 v[122:125], v[160:163], v[184:187], v[122:125]
	v_mfma_f32_16x16x32_bf16 v[110:113], v[152:155], v[192:195], v[110:113]
	v_mfma_f32_16x16x32_bf16 v[106:109], v[160:163], v[192:195], v[106:109]
	v_mfma_f32_16x16x32_bf16 v[94:97], v[152:155], v[200:203], v[94:97]
	v_mfma_f32_16x16x32_bf16 v[90:93], v[160:163], v[200:203], v[90:93]
	v_mfma_f32_16x16x32_bf16 v[78:81], v[152:155], v[208:211], v[78:81]
	v_mfma_f32_16x16x32_bf16 v[74:77], v[160:163], v[208:211], v[74:77]
	v_mfma_f32_16x16x32_bf16 v[126:129], v[156:159], v[188:191], v[126:129]
	v_mfma_f32_16x16x32_bf16 v[122:125], v[164:167], v[188:191], v[122:125]
	v_mfma_f32_16x16x32_bf16 v[110:113], v[156:159], v[196:199], v[110:113]
	v_mfma_f32_16x16x32_bf16 v[106:109], v[164:167], v[196:199], v[106:109]
	v_mfma_f32_16x16x32_bf16 v[94:97], v[156:159], v[204:207], v[94:97]
	v_mfma_f32_16x16x32_bf16 v[90:93], v[164:167], v[204:207], v[90:93]
	v_mfma_f32_16x16x32_bf16 v[78:81], v[156:159], v[212:215], v[78:81]
	v_mfma_f32_16x16x32_bf16 v[74:77], v[164:167], v[212:215], v[74:77]
	s_setprio 0
	s_setprio 1
	v_mfma_f32_16x16x32_bf16 v[118:121], v[168:171], v[184:187], v[118:121]
	v_mfma_f32_16x16x32_bf16 v[114:117], v[176:179], v[184:187], v[114:117]
	v_mfma_f32_16x16x32_bf16 v[102:105], v[168:171], v[192:195], v[102:105]
	v_mfma_f32_16x16x32_bf16 v[98:101], v[176:179], v[192:195], v[98:101]
	v_mfma_f32_16x16x32_bf16 v[86:89], v[168:171], v[200:203], v[86:89]
	v_mfma_f32_16x16x32_bf16 v[82:85], v[176:179], v[200:203], v[82:85]
	v_mfma_f32_16x16x32_bf16 v[70:73], v[168:171], v[208:211], v[70:73]
	v_mfma_f32_16x16x32_bf16 v[66:69], v[176:179], v[208:211], v[66:69]
	v_mfma_f32_16x16x32_bf16 v[118:121], v[172:175], v[188:191], v[118:121]
	v_mfma_f32_16x16x32_bf16 v[114:117], v[180:183], v[188:191], v[114:117]
	v_mfma_f32_16x16x32_bf16 v[102:105], v[172:175], v[196:199], v[102:105]
	v_mfma_f32_16x16x32_bf16 v[98:101], v[180:183], v[196:199], v[98:101]
	v_mfma_f32_16x16x32_bf16 v[86:89], v[172:175], v[204:207], v[86:89]
	v_mfma_f32_16x16x32_bf16 v[82:85], v[180:183], v[204:207], v[82:85]
	v_mfma_f32_16x16x32_bf16 v[70:73], v[172:175], v[212:215], v[70:73]
	v_mfma_f32_16x16x32_bf16 v[66:69], v[180:183], v[212:215], v[66:69]
	s_setprio 0
	s_barrier
	s_add_i32 s49, s40, s30
	s_mov_b32 m0, s49
	ds_read_b128 v[184:187], v151 offset:16384
	ds_read_b128 v[188:191], v228 offset:16384
	ds_read_b128 v[192:195], v151 offset:18432
	ds_read_b128 v[196:199], v228 offset:18432
	ds_read_b128 v[200:203], v151 offset:20480
	ds_read_b128 v[204:207], v228 offset:20480
	ds_read_b128 v[208:211], v151 offset:22528
	ds_read_b128 v[212:215], v228 offset:22528
	global_load_lds_dwordx4 v132, s[22:23]
	s_add_i32 m0, s49, 0x2000
	s_add_u32 s50, s22, 0x80000
	s_addc_u32 s51, s23, 0
	s_add_i32 s49, s41, s30
	global_load_lds_dwordx4 v136, s[22:23]
	s_mov_b32 m0, s49
	s_nop 0
	global_load_lds_dwordx4 v132, s[50:51]
	s_add_i32 m0, s49, 0x2000
	s_nop 0
	global_load_lds_dwordx4 v136, s[50:51]
	s_mov_b32 m0, s19
	s_nop 0
	global_load_lds_dwordx4 v130, s[24:25]
	s_mov_b32 m0, s33
	s_nop 0
	global_load_lds_dwordx4 v134, s[24:25]
	s_waitcnt vmcnt(8)
	s_waitcnt lgkmcnt(0)
	s_barrier
	s_setprio 1
	s_waitcnt lgkmcnt(0)
	v_mfma_f32_16x16x32_bf16 v[62:65], v[152:155], v[184:187], v[62:65]
	v_mfma_f32_16x16x32_bf16 v[58:61], v[160:163], v[184:187], v[58:61]
	v_mfma_f32_16x16x32_bf16 v[46:49], v[152:155], v[192:195], v[46:49]
	v_mfma_f32_16x16x32_bf16 v[42:45], v[160:163], v[192:195], v[42:45]
	v_mfma_f32_16x16x32_bf16 v[30:33], v[152:155], v[200:203], v[30:33]
	v_mfma_f32_16x16x32_bf16 v[26:29], v[160:163], v[200:203], v[26:29]
	v_mfma_f32_16x16x32_bf16 v[14:17], v[152:155], v[208:211], v[14:17]
	v_mfma_f32_16x16x32_bf16 v[10:13], v[160:163], v[208:211], v[10:13]
	v_mfma_f32_16x16x32_bf16 v[62:65], v[156:159], v[188:191], v[62:65]
	v_mfma_f32_16x16x32_bf16 v[58:61], v[164:167], v[188:191], v[58:61]
	v_mfma_f32_16x16x32_bf16 v[46:49], v[156:159], v[196:199], v[46:49]
	v_mfma_f32_16x16x32_bf16 v[42:45], v[164:167], v[196:199], v[42:45]
	v_mfma_f32_16x16x32_bf16 v[30:33], v[156:159], v[204:207], v[30:33]
	v_mfma_f32_16x16x32_bf16 v[26:29], v[164:167], v[204:207], v[26:29]
	v_mfma_f32_16x16x32_bf16 v[14:17], v[156:159], v[212:215], v[14:17]
	v_mfma_f32_16x16x32_bf16 v[10:13], v[164:167], v[212:215], v[10:13]
	s_setprio 0
	s_setprio 1
	v_mfma_f32_16x16x32_bf16 v[54:57], v[168:171], v[184:187], v[54:57]
	v_mfma_f32_16x16x32_bf16 v[50:53], v[176:179], v[184:187], v[50:53]
	v_mfma_f32_16x16x32_bf16 v[38:41], v[168:171], v[192:195], v[38:41]
	v_mfma_f32_16x16x32_bf16 v[34:37], v[176:179], v[192:195], v[34:37]
	v_mfma_f32_16x16x32_bf16 v[22:25], v[168:171], v[200:203], v[22:25]
	v_mfma_f32_16x16x32_bf16 v[18:21], v[176:179], v[200:203], v[18:21]
	v_mfma_f32_16x16x32_bf16 v[6:9], v[168:171], v[208:211], v[6:9]
	v_mfma_f32_16x16x32_bf16 v[2:5], v[176:179], v[208:211], v[2:5]
	v_mfma_f32_16x16x32_bf16 v[54:57], v[172:175], v[188:191], v[54:57]
	v_mfma_f32_16x16x32_bf16 v[50:53], v[180:183], v[188:191], v[50:53]
	v_mfma_f32_16x16x32_bf16 v[38:41], v[172:175], v[196:199], v[38:41]
	v_mfma_f32_16x16x32_bf16 v[34:37], v[180:183], v[196:199], v[34:37]
	v_mfma_f32_16x16x32_bf16 v[22:25], v[172:175], v[204:207], v[22:25]
	v_mfma_f32_16x16x32_bf16 v[18:21], v[180:183], v[204:207], v[18:21]
	v_mfma_f32_16x16x32_bf16 v[6:9], v[172:175], v[212:215], v[6:9]
	v_mfma_f32_16x16x32_bf16 v[2:5], v[180:183], v[212:215], v[2:5]
	s_setprio 0
	s_barrier
	s_add_i32 s49, 0, 0x18000
	s_add_i32 s50, 0, 0x1c000
	v_add_u32_e32 v164, s49, v147
	v_add_u32_e32 v232, s49, v229
	v_add_u32_e32 v180, s50, v147
	v_add_u32_e32 v233, s50, v229
	ds_read_b128 v[152:155], v164
	ds_read_b128 v[156:159], v232
	ds_read_b128 v[160:163], v164 offset:2048
	ds_read_b128 v[164:167], v232 offset:2048
	ds_read_b128 v[168:171], v180
	ds_read_b128 v[172:175], v233
	ds_read_b128 v[176:179], v180 offset:2048
	ds_read_b128 v[180:183], v233 offset:2048
	s_add_u32 s24, s24, 0x80000
	s_addc_u32 s25, s25, 0
	s_add_u32 s100, s24, 0xfff80080
	s_addc_u32 s101, s25, -1
	s_mov_b32 m0, s34
	ds_read_b128 v[184:187], v151 offset:32768
	ds_read_b128 v[188:191], v228 offset:32768
	ds_read_b128 v[192:195], v151 offset:34816
	ds_read_b128 v[196:199], v228 offset:34816
	ds_read_b128 v[200:203], v151 offset:36864
	ds_read_b128 v[204:207], v228 offset:36864
	ds_read_b128 v[208:211], v151 offset:38912
	ds_read_b128 v[212:215], v228 offset:38912
	global_load_lds_dwordx4 v130, s[24:25]
	s_mov_b32 m0, s35
	s_nop 0
	global_load_lds_dwordx4 v134, s[24:25]
	s_waitcnt vmcnt(8)
	s_waitcnt lgkmcnt(0)
	s_barrier
	s_setprio 1
	s_waitcnt lgkmcnt(0)
	v_mfma_f32_16x16x32_bf16 v[126:129], v[152:155], v[184:187], v[126:129]
	v_mfma_f32_16x16x32_bf16 v[122:125], v[160:163], v[184:187], v[122:125]
	v_mfma_f32_16x16x32_bf16 v[110:113], v[152:155], v[192:195], v[110:113]
	v_mfma_f32_16x16x32_bf16 v[106:109], v[160:163], v[192:195], v[106:109]
	v_mfma_f32_16x16x32_bf16 v[94:97], v[152:155], v[200:203], v[94:97]
	v_mfma_f32_16x16x32_bf16 v[90:93], v[160:163], v[200:203], v[90:93]
	v_mfma_f32_16x16x32_bf16 v[78:81], v[152:155], v[208:211], v[78:81]
	v_mfma_f32_16x16x32_bf16 v[74:77], v[160:163], v[208:211], v[74:77]
	v_mfma_f32_16x16x32_bf16 v[126:129], v[156:159], v[188:191], v[126:129]
	v_mfma_f32_16x16x32_bf16 v[122:125], v[164:167], v[188:191], v[122:125]
	v_mfma_f32_16x16x32_bf16 v[110:113], v[156:159], v[196:199], v[110:113]
	v_mfma_f32_16x16x32_bf16 v[106:109], v[164:167], v[196:199], v[106:109]
	v_mfma_f32_16x16x32_bf16 v[94:97], v[156:159], v[204:207], v[94:97]
	v_mfma_f32_16x16x32_bf16 v[90:93], v[164:167], v[204:207], v[90:93]
	v_mfma_f32_16x16x32_bf16 v[78:81], v[156:159], v[212:215], v[78:81]
	v_mfma_f32_16x16x32_bf16 v[74:77], v[164:167], v[212:215], v[74:77]
	s_setprio 0
	s_setprio 1
	v_mfma_f32_16x16x32_bf16 v[118:121], v[168:171], v[184:187], v[118:121]
	v_mfma_f32_16x16x32_bf16 v[114:117], v[176:179], v[184:187], v[114:117]
	v_mfma_f32_16x16x32_bf16 v[102:105], v[168:171], v[192:195], v[102:105]
	v_mfma_f32_16x16x32_bf16 v[98:101], v[176:179], v[192:195], v[98:101]
	v_mfma_f32_16x16x32_bf16 v[86:89], v[168:171], v[200:203], v[86:89]
	v_mfma_f32_16x16x32_bf16 v[82:85], v[176:179], v[200:203], v[82:85]
	v_mfma_f32_16x16x32_bf16 v[70:73], v[168:171], v[208:211], v[70:73]
	v_mfma_f32_16x16x32_bf16 v[66:69], v[176:179], v[208:211], v[66:69]
	v_mfma_f32_16x16x32_bf16 v[118:121], v[172:175], v[188:191], v[118:121]
	v_mfma_f32_16x16x32_bf16 v[114:117], v[180:183], v[188:191], v[114:117]
	v_mfma_f32_16x16x32_bf16 v[102:105], v[172:175], v[196:199], v[102:105]
	v_mfma_f32_16x16x32_bf16 v[98:101], v[180:183], v[196:199], v[98:101]
	v_mfma_f32_16x16x32_bf16 v[86:89], v[172:175], v[204:207], v[86:89]
	v_mfma_f32_16x16x32_bf16 v[82:85], v[180:183], v[204:207], v[82:85]
	v_mfma_f32_16x16x32_bf16 v[70:73], v[172:175], v[212:215], v[70:73]
	v_mfma_f32_16x16x32_bf16 v[66:69], v[180:183], v[212:215], v[66:69]
	s_setprio 0
	s_barrier
	s_add_i32 s24, s49, s30
	s_mov_b32 m0, s24
	ds_read_b128 v[184:187], v151 offset:49152
	ds_read_b128 v[188:191], v228 offset:49152
	ds_read_b128 v[192:195], v151 offset:51200
	ds_read_b128 v[196:199], v228 offset:51200
	ds_read_b128 v[200:203], v151 offset:53248
	ds_read_b128 v[204:207], v228 offset:53248
	ds_read_b128 v[208:211], v151 offset:55296
	ds_read_b128 v[212:215], v228 offset:55296
	s_add_u32 s98, s22, 0x80
	s_addc_u32 s99, s23, 0
	global_load_lds_dwordx4 v132, s[98:99]
	s_add_i32 m0, s24, 0x2000
	s_add_u32 s22, s22, 0x80080
	s_addc_u32 s23, s23, 0
	s_add_i32 s24, s50, s30
	global_load_lds_dwordx4 v136, s[98:99]
	s_mov_b32 m0, s24
	s_nop 0
	global_load_lds_dwordx4 v132, s[22:23]
	s_add_i32 m0, s24, 0x2000
	s_nop 0
	global_load_lds_dwordx4 v136, s[22:23]
	s_mov_b32 m0, s38
	s_nop 0
	global_load_lds_dwordx4 v130, s[100:101]
	s_mov_b32 m0, s39
	s_nop 0
	global_load_lds_dwordx4 v134, s[100:101]
	s_waitcnt vmcnt(8)
	s_waitcnt lgkmcnt(0)
	s_barrier
	s_setprio 1
	s_waitcnt lgkmcnt(0)
	v_mfma_f32_16x16x32_bf16 v[62:65], v[152:155], v[184:187], v[62:65]
	v_mfma_f32_16x16x32_bf16 v[58:61], v[160:163], v[184:187], v[58:61]
	v_mfma_f32_16x16x32_bf16 v[46:49], v[152:155], v[192:195], v[46:49]
	v_mfma_f32_16x16x32_bf16 v[42:45], v[160:163], v[192:195], v[42:45]
	v_mfma_f32_16x16x32_bf16 v[30:33], v[152:155], v[200:203], v[30:33]
	v_mfma_f32_16x16x32_bf16 v[26:29], v[160:163], v[200:203], v[26:29]
	v_mfma_f32_16x16x32_bf16 v[14:17], v[152:155], v[208:211], v[14:17]
	v_mfma_f32_16x16x32_bf16 v[10:13], v[160:163], v[208:211], v[10:13]
	v_mfma_f32_16x16x32_bf16 v[62:65], v[156:159], v[188:191], v[62:65]
	v_mfma_f32_16x16x32_bf16 v[58:61], v[164:167], v[188:191], v[58:61]
	v_mfma_f32_16x16x32_bf16 v[46:49], v[156:159], v[196:199], v[46:49]
	v_mfma_f32_16x16x32_bf16 v[42:45], v[164:167], v[196:199], v[42:45]
	v_mfma_f32_16x16x32_bf16 v[30:33], v[156:159], v[204:207], v[30:33]
	v_mfma_f32_16x16x32_bf16 v[26:29], v[164:167], v[204:207], v[26:29]
	v_mfma_f32_16x16x32_bf16 v[14:17], v[156:159], v[212:215], v[14:17]
	v_mfma_f32_16x16x32_bf16 v[10:13], v[164:167], v[212:215], v[10:13]
	s_setprio 0
	s_setprio 1
	v_mfma_f32_16x16x32_bf16 v[54:57], v[168:171], v[184:187], v[54:57]
	v_mfma_f32_16x16x32_bf16 v[50:53], v[176:179], v[184:187], v[50:53]
	v_mfma_f32_16x16x32_bf16 v[38:41], v[168:171], v[192:195], v[38:41]
	v_mfma_f32_16x16x32_bf16 v[34:37], v[176:179], v[192:195], v[34:37]
	v_mfma_f32_16x16x32_bf16 v[22:25], v[168:171], v[200:203], v[22:25]
	v_mfma_f32_16x16x32_bf16 v[18:21], v[176:179], v[200:203], v[18:21]
	v_mfma_f32_16x16x32_bf16 v[6:9], v[168:171], v[208:211], v[6:9]
	v_mfma_f32_16x16x32_bf16 v[2:5], v[176:179], v[208:211], v[2:5]
	v_mfma_f32_16x16x32_bf16 v[54:57], v[172:175], v[188:191], v[54:57]
	v_mfma_f32_16x16x32_bf16 v[50:53], v[180:183], v[188:191], v[50:53]
	v_mfma_f32_16x16x32_bf16 v[38:41], v[172:175], v[196:199], v[38:41]
	v_mfma_f32_16x16x32_bf16 v[34:37], v[180:183], v[196:199], v[34:37]
	v_mfma_f32_16x16x32_bf16 v[22:25], v[172:175], v[204:207], v[22:25]
	v_mfma_f32_16x16x32_bf16 v[18:21], v[180:183], v[204:207], v[18:21]
	v_mfma_f32_16x16x32_bf16 v[6:9], v[172:175], v[212:215], v[6:9]
	v_mfma_f32_16x16x32_bf16 v[2:5], v[180:183], v[212:215], v[2:5]
	s_setprio 0
	s_barrier
	s_add_i32 s48, s48, 2
	s_add_u32 s20, s20, 0x100
	s_addc_u32 s21, s21, 0
	s_add_u32 s46, s46, 0x100
	s_addc_u32 s47, s47, 0
	s_cmp_gt_u32 s48, 29
	s_cbranch_scc0 .LBB0_1135
	v_readlane_b32 s44, v254, 52
	s_and_b64 vcc, exec, s[8:9]
	v_readlane_b32 s45, v254, 53
	v_readlane_b32 s46, v254, 54
	v_readlane_b32 s47, v254, 55
	s_cbranch_vccz .LBB0_1138
	s_barrier
